# one static s_setprio 1 for waves 4-7 at kernel entry (younger half), no other priority changes
# speedup vs baseline: 1.2291x; 1.0032x over previous
_Z10fwd_kernel6Params:
	s_mov_b64 s[92:93], s[0:1]
	v_readfirstlane_b32 s100, v0
	s_nop 3
	s_and_b32 s100, s100, 0x3ff
	s_lshr_b32 s100, s100, 6
	s_cmp_ge_u32 s100, 4
	s_cbranch_scc0 .Lprio_done
	s_setprio 1
.Lprio_done:
	s_add_u32 s0, s92, 0xc8
	s_load_dword s3, s[92:93], 0xc8
	s_addc_u32 s1, s93, 0
	v_and_b32_e32 v1, 0x3ff, v0
	v_writelane_b32 v254, s0, 0
	v_readfirstlane_b32 s31, v1
	v_cmp_eq_u32_e64 s[4:5], 0, v1
	v_writelane_b32 v254, s1, 1
	s_getreg_b32 s0, hwreg(HW_REG_XCC_ID, 0, 4)
	s_and_b32 s30, s0, 15
	s_mov_b64 s[0:1], exec
	v_writelane_b32 v254, s4, 2
	s_nop 1
	v_writelane_b32 v254, s5, 3
	s_and_b64 s[4:5], s[0:1], s[4:5]
	s_mov_b64 exec, s[4:5]
	s_cbranch_execz .LBB0_3
	s_add_i32 s6, 0, 0x20000
	v_mov_b32_e32 v2, 0
	v_mov_b32_e32 v3, s6
	s_add_i32 s6, 0, 0x20004
	s_mov_b64 s[4:5], exec
	ds_write_b32 v3, v2
	v_mov_b32_e32 v3, s6
	ds_write_b32 v3, v2
	v_mbcnt_lo_u32_b32 v2, s4, 0
	v_mbcnt_hi_u32_b32 v2, s5, v2
	v_cmp_eq_u32_e32 vcc, 0, v2
	s_and_b64 s[6:7], exec, vcc
	s_mov_b64 exec, s[6:7]
	s_cbranch_execz .LBB0_3
	s_load_dwordx2 s[6:7], s[92:93], 0x98
	s_lshl_b32 s8, s30, 8
	v_mov_b32_e32 v2, 0x1f3d0000
	s_waitcnt lgkmcnt(0)
	s_add_u32 s6, s6, s8
	s_addc_u32 s7, s7, 0
	s_bcnt1_i32_b64 s4, s[4:5]
	v_mov_b32_e32 v3, s4
	global_atomic_add v2, v3, s[6:7] offset:1024
